# removed redundant vmcnt(0) before ds_read at the head of all 9 GEMM K-loops so LDS-DMA prefetch overlaps MFMAs
# speedup vs baseline: 1.0312x; 1.0312x over previous
; __device__ __forceinline__ f32x16 mfma32(bf16x8 a, bf16x8 b, f32x16 c) { return __builtin_amdgcn_mfma_f32_32x32x16_bf16(a, b, c, 0, 0, 0); }
; template <bool SW>
; __device__ __forceinline__ void gemm_mainloop(const bf16_t* __restrict__ A, int lda, const bf16_t* __restrict__ Bt, int ldb, int K,
;                                               f32x16 (&acc)[2][2], char* lds, int kstart) {
;     ...
;   for (int kt = 0; kt < nk; ++kt) {
;     const bool more = (kt + 1 < nk);
;     if (more) {
;       char* d = ldst + ((kt + 1) & 1) * GEMM_BUF;
;       const int ko = ((kt + 1 + kstart) & (nk - 1)) * 64;
; #pragma unroll
;       for (int i = 0; i < 4; ++i) { glds16(ap[i] + ko, d + i * 1024); glds16(bp[i] + ko, d + 16384 + i * 1024); }
;     }
;     const char* base = lds + (kt & 1) * GEMM_BUF;
; #pragma unroll
;     for (int ks = 0; ks < 4; ++ks) {
;       const int co = ((2 * ks + hh) ^ swz) * 16;
;       bf16x8 a0 = *(const bf16x8*)(base + roffA + co), a1 = *(const bf16x8*)(base + roffA + 32 * 128 + co);
;       bf16x8 b0 = *(const bf16x8*)(base + roffB + co), b1 = *(const bf16x8*)(base + roffB + 32 * 128 + co);
;       if (SW) {
;         acc[0][0] = mfma32(b0, a0, acc[0][0]); acc[0][1] = mfma32(b1, a0, acc[0][1]);
;         acc[1][0] = mfma32(b0, a1, acc[1][0]); acc[1][1] = mfma32(b1, a1, acc[1][1]);
;       } else {
;         acc[0][0] = mfma32(a0, b0, acc[0][0]); acc[0][1] = mfma32(a0, b1, acc[0][1]);
;         acc[1][0] = mfma32(a1, b0, acc[1][0]); acc[1][1] = mfma32(a1, b1, acc[1][1]);
;       }
;     }
;     asm volatile("s_waitcnt vmcnt(0)" ::: "memory");
;     __syncthreads();
;   }
.LBB0_175:
	s_and_b32 s0, s34, 0x8000
	v_or_b32_e32 v109, s0, v150
	v_add_u32_e32 v111, v109, v151
	ds_read_b128 v[138:141], v111 offset:16384
	ds_read_b128 v[168:171], v111 offset:20480
	v_add_u32_e32 v113, s0, v149
	v_add_u32_e32 v115, v113, v151
	ds_read_b128 v[164:167], v115
	v_add_u32_e32 v111, v109, v152
	s_add_i32 s3, s3, 1
	s_add_i32 s2, s2, 64
	s_cmp_lg_u32 s3, 16
	s_waitcnt lgkmcnt(0)
	v_mfma_f32_32x32x16_bf16 v[48:63], v[138:141], v[164:167], v[48:63]
	s_mov_b32 s34, s35
	v_mfma_f32_32x32x16_bf16 v[32:47], v[168:171], v[164:167], v[32:47]
	ds_read_b128 v[164:167], v115 offset:4096
	v_add_u32_e32 v115, v113, v152
	s_waitcnt lgkmcnt(0)
	v_mfma_f32_32x32x16_bf16 v[16:31], v[138:141], v[164:167], v[16:31]
	ds_read_b128 v[138:141], v111 offset:16384
	v_mfma_f32_32x32x16_bf16 v[0:15], v[168:171], v[164:167], v[0:15]
	ds_read_b128 v[168:171], v111 offset:20480
	ds_read_b128 v[164:167], v115
	v_add_u32_e32 v111, v109, v153
	v_add_u32_e32 v109, v109, v154
	s_waitcnt lgkmcnt(0)
	v_mfma_f32_32x32x16_bf16 v[48:63], v[138:141], v[164:167], v[48:63]
	v_mfma_f32_32x32x16_bf16 v[32:47], v[168:171], v[164:167], v[32:47]
	ds_read_b128 v[164:167], v115 offset:4096
	v_add_u32_e32 v115, v113, v153
	s_waitcnt lgkmcnt(0)
	v_mfma_f32_32x32x16_bf16 v[16:31], v[138:141], v[164:167], v[16:31]
	ds_read_b128 v[138:141], v111 offset:16384
	v_mfma_f32_32x32x16_bf16 v[0:15], v[168:171], v[164:167], v[0:15]
	ds_read_b128 v[168:171], v111 offset:20480
	ds_read_b128 v[164:167], v115
	v_add_u32_e32 v111, v113, v154
	s_waitcnt lgkmcnt(0)
	v_mfma_f32_32x32x16_bf16 v[48:63], v[138:141], v[164:167], v[48:63]
	v_mfma_f32_32x32x16_bf16 v[32:47], v[168:171], v[164:167], v[32:47]
	ds_read_b128 v[164:167], v115 offset:4096
	s_waitcnt lgkmcnt(0)
	v_mfma_f32_32x32x16_bf16 v[16:31], v[138:141], v[164:167], v[16:31]
	ds_read_b128 v[138:141], v109 offset:16384
	v_mfma_f32_32x32x16_bf16 v[0:15], v[168:171], v[164:167], v[0:15]
	ds_read_b128 v[168:171], v109 offset:20480
	ds_read_b128 v[164:167], v111
	s_waitcnt lgkmcnt(0)
	v_mfma_f32_32x32x16_bf16 v[48:63], v[138:141], v[164:167], v[48:63]
	v_mfma_f32_32x32x16_bf16 v[32:47], v[168:171], v[164:167], v[32:47]
	ds_read_b128 v[164:167], v111 offset:4096
	s_waitcnt vmcnt(0)
	s_waitcnt lgkmcnt(0)
	s_barrier
	v_mfma_f32_32x32x16_bf16 v[16:31], v[138:141], v[164:167], v[16:31]
	v_mfma_f32_32x32x16_bf16 v[0:15], v[168:171], v[164:167], v[0:15]
	s_cbranch_scc0 .LBB0_180

; __device__ __forceinline__ f32x16 mfma32(bf16x8 a, bf16x8 b, f32x16 c) { return __builtin_amdgcn_mfma_f32_32x32x16_bf16(a, b, c, 0, 0, 0); }
; template <bool SW>
; __device__ __forceinline__ void gemm_mainloop(const bf16_t* __restrict__ A, int lda, const bf16_t* __restrict__ Bt, int ldb, int K,
;                                               f32x16 (&acc)[2][2], char* lds, int kstart) {
;     ...
;   for (int kt = 0; kt < nk; ++kt) {
;     const bool more = (kt + 1 < nk);
;     if (more) {
;       char* d = ldst + ((kt + 1) & 1) * GEMM_BUF;
;       const int ko = ((kt + 1 + kstart) & (nk - 1)) * 64;
; #pragma unroll
;       for (int i = 0; i < 4; ++i) { glds16(ap[i] + ko, d + i * 1024); glds16(bp[i] + ko, d + 16384 + i * 1024); }
;     }
;     const char* base = lds + (kt & 1) * GEMM_BUF;
; #pragma unroll
;     for (int ks = 0; ks < 4; ++ks) {
;       const int co = ((2 * ks + hh) ^ swz) * 16;
;       bf16x8 a0 = *(const bf16x8*)(base + roffA + co), a1 = *(const bf16x8*)(base + roffA + 32 * 128 + co);
;       bf16x8 b0 = *(const bf16x8*)(base + roffB + co), b1 = *(const bf16x8*)(base + roffB + 32 * 128 + co);
;       if (SW) {
;         acc[0][0] = mfma32(b0, a0, acc[0][0]); acc[0][1] = mfma32(b1, a0, acc[0][1]);
;         acc[1][0] = mfma32(b0, a1, acc[1][0]); acc[1][1] = mfma32(b1, a1, acc[1][1]);
;       } else {
;         acc[0][0] = mfma32(a0, b0, acc[0][0]); acc[0][1] = mfma32(a0, b1, acc[0][1]);
;         acc[1][0] = mfma32(a1, b0, acc[1][0]); acc[1][1] = mfma32(a1, b1, acc[1][1]);
;       }
;     }
;     asm volatile("s_waitcnt vmcnt(0)" ::: "memory");
;     __syncthreads();
;   }
.LBB0_263:
	s_and_b32 s0, s34, 0x8000
	v_add_u32_e32 v109, s0, v149
	v_add_u32_e32 v111, v109, v151
	ds_read_b128 v[124:127], v111
	v_or_b32_e32 v113, s0, v150
	v_add_u32_e32 v115, v113, v151
	ds_read_b128 v[138:141], v115 offset:16384
	ds_read_b128 v[164:167], v115 offset:20480
	v_add_u32_e32 v115, v113, v152
	s_add_i32 s3, s3, 1
	s_add_i32 s2, s2, 64
	s_cmp_lg_u32 s3, 16
	s_waitcnt lgkmcnt(0)
	v_mfma_f32_32x32x16_bf16 v[48:63], v[124:127], v[138:141], v[48:63]
	s_mov_b32 s34, s35
	v_mfma_f32_32x32x16_bf16 v[32:47], v[124:127], v[164:167], v[32:47]
	ds_read_b128 v[124:127], v111 offset:4096
	v_add_u32_e32 v111, v109, v152
	s_waitcnt lgkmcnt(0)
	v_mfma_f32_32x32x16_bf16 v[16:31], v[124:127], v[138:141], v[16:31]
	ds_read_b128 v[138:141], v115 offset:16384
	v_mfma_f32_32x32x16_bf16 v[0:15], v[124:127], v[164:167], v[0:15]
	ds_read_b128 v[124:127], v111
	ds_read_b128 v[164:167], v115 offset:20480
	v_add_u32_e32 v115, v113, v153
	s_waitcnt lgkmcnt(1)
	v_mfma_f32_32x32x16_bf16 v[48:63], v[124:127], v[138:141], v[48:63]
	s_waitcnt lgkmcnt(0)
	v_mfma_f32_32x32x16_bf16 v[32:47], v[124:127], v[164:167], v[32:47]
	ds_read_b128 v[124:127], v111 offset:4096
	v_add_u32_e32 v111, v109, v153
	v_add_u32_e32 v109, v109, v154
	s_waitcnt lgkmcnt(0)
	v_mfma_f32_32x32x16_bf16 v[16:31], v[124:127], v[138:141], v[16:31]
	ds_read_b128 v[138:141], v115 offset:16384
	v_mfma_f32_32x32x16_bf16 v[0:15], v[124:127], v[164:167], v[0:15]
	ds_read_b128 v[124:127], v111
	ds_read_b128 v[164:167], v115 offset:20480
	s_waitcnt lgkmcnt(1)
	v_mfma_f32_32x32x16_bf16 v[48:63], v[124:127], v[138:141], v[48:63]
	s_waitcnt lgkmcnt(0)
	v_mfma_f32_32x32x16_bf16 v[32:47], v[124:127], v[164:167], v[32:47]
	ds_read_b128 v[124:127], v111 offset:4096
	v_add_u32_e32 v111, v113, v154
	s_waitcnt lgkmcnt(0)
	v_mfma_f32_32x32x16_bf16 v[16:31], v[124:127], v[138:141], v[16:31]
	ds_read_b128 v[138:141], v111 offset:16384
	v_mfma_f32_32x32x16_bf16 v[0:15], v[124:127], v[164:167], v[0:15]
	ds_read_b128 v[124:127], v109
	ds_read_b128 v[164:167], v111 offset:20480
	s_waitcnt lgkmcnt(1)
	v_mfma_f32_32x32x16_bf16 v[48:63], v[124:127], v[138:141], v[48:63]
	s_waitcnt lgkmcnt(0)
	v_mfma_f32_32x32x16_bf16 v[32:47], v[124:127], v[164:167], v[32:47]
	ds_read_b128 v[124:127], v109 offset:4096
	s_waitcnt vmcnt(0)
	s_waitcnt lgkmcnt(0)
	s_barrier
	v_mfma_f32_32x32x16_bf16 v[16:31], v[124:127], v[138:141], v[16:31]
	v_mfma_f32_32x32x16_bf16 v[0:15], v[124:127], v[164:167], v[0:15]
	s_cbranch_scc0 .LBB0_268

; __device__ __forceinline__ f32x16 mfma32(bf16x8 a, bf16x8 b, f32x16 c) { return __builtin_amdgcn_mfma_f32_32x32x16_bf16(a, b, c, 0, 0, 0); }
; template <bool SW>
; __device__ __forceinline__ void gemm_mainloop(const bf16_t* __restrict__ A, int lda, const bf16_t* __restrict__ Bt, int ldb, int K,
;                                               f32x16 (&acc)[2][2], char* lds, int kstart) {
;     ...
;   for (int kt = 0; kt < nk; ++kt) {
;     const bool more = (kt + 1 < nk);
;     if (more) {
;       char* d = ldst + ((kt + 1) & 1) * GEMM_BUF;
;       const int ko = ((kt + 1 + kstart) & (nk - 1)) * 64;
; #pragma unroll
;       for (int i = 0; i < 4; ++i) { glds16(ap[i] + ko, d + i * 1024); glds16(bp[i] + ko, d + 16384 + i * 1024); }
;     }
;     const char* base = lds + (kt & 1) * GEMM_BUF;
; #pragma unroll
;     for (int ks = 0; ks < 4; ++ks) {
;       const int co = ((2 * ks + hh) ^ swz) * 16;
;       bf16x8 a0 = *(const bf16x8*)(base + roffA + co), a1 = *(const bf16x8*)(base + roffA + 32 * 128 + co);
;       bf16x8 b0 = *(const bf16x8*)(base + roffB + co), b1 = *(const bf16x8*)(base + roffB + 32 * 128 + co);
;       if (SW) {
;         acc[0][0] = mfma32(b0, a0, acc[0][0]); acc[0][1] = mfma32(b1, a0, acc[0][1]);
;         acc[1][0] = mfma32(b0, a1, acc[1][0]); acc[1][1] = mfma32(b1, a1, acc[1][1]);
;       } else {
;         acc[0][0] = mfma32(a0, b0, acc[0][0]); acc[0][1] = mfma32(a0, b1, acc[0][1]);
;         acc[1][0] = mfma32(a1, b0, acc[1][0]); acc[1][1] = mfma32(a1, b1, acc[1][1]);
;       }
;     }
;     asm volatile("s_waitcnt vmcnt(0)" ::: "memory");
;     __syncthreads();
;   }
.LBB0_545:
	v_add_u32_e32 v77, s43, v117
	v_add_u32_e32 v85, v77, v119
	ds_read_b128 v[142:145], v85
	v_add_u32_e32 v87, s43, v118
	v_add_u32_e32 v89, v87, v119
	ds_read_b128 v[148:151], v89 offset:16384
	ds_read_b128 v[152:155], v89 offset:20480
	v_add_u32_e32 v89, v87, v120
	s_mov_b32 s43, 0x8000
	s_mov_b64 s[2:3], 0
	s_andn2_b64 vcc, exec, s[0:1]
	s_waitcnt lgkmcnt(0)
	v_mfma_f32_32x32x16_bf16 v[48:63], v[142:145], v[148:151], v[48:63]
	s_mov_b64 s[0:1], -1
	v_mfma_f32_32x32x16_bf16 v[32:47], v[142:145], v[152:155], v[32:47]
	ds_read_b128 v[142:145], v85 offset:4096
	v_add_u32_e32 v85, v77, v120
	s_waitcnt lgkmcnt(0)
	v_mfma_f32_32x32x16_bf16 v[16:31], v[142:145], v[148:151], v[16:31]
	ds_read_b128 v[148:151], v89 offset:16384
	v_mfma_f32_32x32x16_bf16 v[0:15], v[142:145], v[152:155], v[0:15]
	ds_read_b128 v[142:145], v85
	ds_read_b128 v[152:155], v89 offset:20480
	v_add_u32_e32 v89, v87, v121
	s_waitcnt lgkmcnt(1)
	v_mfma_f32_32x32x16_bf16 v[48:63], v[142:145], v[148:151], v[48:63]
	s_waitcnt lgkmcnt(0)
	v_mfma_f32_32x32x16_bf16 v[32:47], v[142:145], v[152:155], v[32:47]
	ds_read_b128 v[142:145], v85 offset:4096
	v_add_u32_e32 v85, v77, v121
	v_add_u32_e32 v77, v77, v122
	s_waitcnt lgkmcnt(0)
	v_mfma_f32_32x32x16_bf16 v[16:31], v[142:145], v[148:151], v[16:31]
	ds_read_b128 v[148:151], v89 offset:16384
	v_mfma_f32_32x32x16_bf16 v[0:15], v[142:145], v[152:155], v[0:15]
	ds_read_b128 v[142:145], v85
	ds_read_b128 v[152:155], v89 offset:20480
	s_waitcnt lgkmcnt(1)
	v_mfma_f32_32x32x16_bf16 v[48:63], v[142:145], v[148:151], v[48:63]
	s_waitcnt lgkmcnt(0)
	v_mfma_f32_32x32x16_bf16 v[32:47], v[142:145], v[152:155], v[32:47]
	ds_read_b128 v[142:145], v85 offset:4096
	v_add_u32_e32 v85, v87, v122
	s_waitcnt lgkmcnt(0)
	v_mfma_f32_32x32x16_bf16 v[16:31], v[142:145], v[148:151], v[16:31]
	ds_read_b128 v[148:151], v85 offset:16384
	v_mfma_f32_32x32x16_bf16 v[0:15], v[142:145], v[152:155], v[0:15]
	ds_read_b128 v[142:145], v77
	ds_read_b128 v[152:155], v85 offset:20480
	s_waitcnt lgkmcnt(1)
	v_mfma_f32_32x32x16_bf16 v[48:63], v[142:145], v[148:151], v[48:63]
	s_waitcnt lgkmcnt(0)
	v_mfma_f32_32x32x16_bf16 v[32:47], v[142:145], v[152:155], v[32:47]
	ds_read_b128 v[142:145], v77 offset:4096
	s_waitcnt vmcnt(0)
	s_waitcnt lgkmcnt(0)
	s_barrier
	v_mfma_f32_32x32x16_bf16 v[16:31], v[142:145], v[148:151], v[16:31]
	v_mfma_f32_32x32x16_bf16 v[0:15], v[142:145], v[152:155], v[0:15]
	s_cbranch_vccz .LBB0_548

; __device__ __forceinline__ f32x16 mfma32(bf16x8 a, bf16x8 b, f32x16 c) { return __builtin_amdgcn_mfma_f32_32x32x16_bf16(a, b, c, 0, 0, 0); }
; template <bool SW>
; __device__ __forceinline__ void gemm_mainloop(const bf16_t* __restrict__ A, int lda, const bf16_t* __restrict__ Bt, int ldb, int K,
;                                               f32x16 (&acc)[2][2], char* lds, int kstart) {
;     ...
;   for (int kt = 0; kt < nk; ++kt) {
;     const bool more = (kt + 1 < nk);
;     if (more) {
;       char* d = ldst + ((kt + 1) & 1) * GEMM_BUF;
;       const int ko = ((kt + 1 + kstart) & (nk - 1)) * 64;
; #pragma unroll
;       for (int i = 0; i < 4; ++i) { glds16(ap[i] + ko, d + i * 1024); glds16(bp[i] + ko, d + 16384 + i * 1024); }
;     }
;     const char* base = lds + (kt & 1) * GEMM_BUF;
; #pragma unroll
;     for (int ks = 0; ks < 4; ++ks) {
;       const int co = ((2 * ks + hh) ^ swz) * 16;
;       bf16x8 a0 = *(const bf16x8*)(base + roffA + co), a1 = *(const bf16x8*)(base + roffA + 32 * 128 + co);
;       bf16x8 b0 = *(const bf16x8*)(base + roffB + co), b1 = *(const bf16x8*)(base + roffB + 32 * 128 + co);
;       if (SW) {
;         acc[0][0] = mfma32(b0, a0, acc[0][0]); acc[0][1] = mfma32(b1, a0, acc[0][1]);
;         acc[1][0] = mfma32(b0, a1, acc[1][0]); acc[1][1] = mfma32(b1, a1, acc[1][1]);
;       } else {
;         acc[0][0] = mfma32(a0, b0, acc[0][0]); acc[0][1] = mfma32(a0, b1, acc[0][1]);
;         acc[1][0] = mfma32(a1, b0, acc[1][0]); acc[1][1] = mfma32(a1, b1, acc[1][1]);
;       }
;     }
;     asm volatile("s_waitcnt vmcnt(0)" ::: "memory");
;     __syncthreads();
;   }
.LBB0_555:
	v_add_u32_e32 v77, s10, v118
	v_add_u32_e32 v85, v77, v119
	ds_read_b128 v[108:111], v85 offset:16384
	ds_read_b128 v[148:151], v85 offset:20480
	v_add_u32_e32 v87, s10, v117
	v_add_u32_e32 v89, v87, v119
	ds_read_b128 v[142:145], v89
	v_add_u32_e32 v85, v77, v120
	s_mov_b32 s10, 0x8000
	s_mov_b64 s[2:3], 0
	s_andn2_b64 vcc, exec, s[0:1]
	s_waitcnt lgkmcnt(0)
	v_mfma_f32_32x32x16_bf16 v[48:63], v[108:111], v[142:145], v[48:63]
	s_mov_b64 s[0:1], -1
	v_mfma_f32_32x32x16_bf16 v[32:47], v[148:151], v[142:145], v[32:47]
	ds_read_b128 v[142:145], v89 offset:4096
	v_add_u32_e32 v89, v87, v120
	s_waitcnt lgkmcnt(0)
	v_mfma_f32_32x32x16_bf16 v[16:31], v[108:111], v[142:145], v[16:31]
	ds_read_b128 v[108:111], v85 offset:16384
	v_mfma_f32_32x32x16_bf16 v[0:15], v[148:151], v[142:145], v[0:15]
	ds_read_b128 v[148:151], v85 offset:20480
	ds_read_b128 v[142:145], v89
	v_add_u32_e32 v85, v77, v121
	v_add_u32_e32 v77, v77, v122
	s_waitcnt lgkmcnt(0)
	v_mfma_f32_32x32x16_bf16 v[48:63], v[108:111], v[142:145], v[48:63]
	v_mfma_f32_32x32x16_bf16 v[32:47], v[148:151], v[142:145], v[32:47]
	ds_read_b128 v[142:145], v89 offset:4096
	v_add_u32_e32 v89, v87, v121
	s_waitcnt lgkmcnt(0)
	v_mfma_f32_32x32x16_bf16 v[16:31], v[108:111], v[142:145], v[16:31]
	ds_read_b128 v[108:111], v85 offset:16384
	v_mfma_f32_32x32x16_bf16 v[0:15], v[148:151], v[142:145], v[0:15]
	ds_read_b128 v[148:151], v85 offset:20480
	ds_read_b128 v[142:145], v89
	v_add_u32_e32 v85, v87, v122
	s_waitcnt lgkmcnt(0)
	v_mfma_f32_32x32x16_bf16 v[48:63], v[108:111], v[142:145], v[48:63]
	v_mfma_f32_32x32x16_bf16 v[32:47], v[148:151], v[142:145], v[32:47]
	ds_read_b128 v[142:145], v89 offset:4096
	s_waitcnt lgkmcnt(0)
	v_mfma_f32_32x32x16_bf16 v[16:31], v[108:111], v[142:145], v[16:31]
	ds_read_b128 v[108:111], v77 offset:16384
	v_mfma_f32_32x32x16_bf16 v[0:15], v[148:151], v[142:145], v[0:15]
	ds_read_b128 v[148:151], v77 offset:20480
	ds_read_b128 v[142:145], v85
	s_waitcnt lgkmcnt(0)
	v_mfma_f32_32x32x16_bf16 v[48:63], v[108:111], v[142:145], v[48:63]
	v_mfma_f32_32x32x16_bf16 v[32:47], v[148:151], v[142:145], v[32:47]
	ds_read_b128 v[142:145], v85 offset:4096
	s_waitcnt vmcnt(0)
	s_waitcnt lgkmcnt(0)
	s_barrier
	v_mfma_f32_32x32x16_bf16 v[16:31], v[108:111], v[142:145], v[16:31]
	v_mfma_f32_32x32x16_bf16 v[0:15], v[148:151], v[142:145], v[0:15]
	s_cbranch_vccz .LBB0_558

; __device__ __forceinline__ f32x16 mfma32(bf16x8 a, bf16x8 b, f32x16 c) { return __builtin_amdgcn_mfma_f32_32x32x16_bf16(a, b, c, 0, 0, 0); }
; template <bool SW>
; __device__ __forceinline__ void gemm_mainloop(const bf16_t* __restrict__ A, int lda, const bf16_t* __restrict__ Bt, int ldb, int K,
;                                               f32x16 (&acc)[2][2], char* lds, int kstart) {
;     ...
;   for (int kt = 0; kt < nk; ++kt) {
;     const bool more = (kt + 1 < nk);
;     if (more) {
;       char* d = ldst + ((kt + 1) & 1) * GEMM_BUF;
;       const int ko = ((kt + 1 + kstart) & (nk - 1)) * 64;
; #pragma unroll
;       for (int i = 0; i < 4; ++i) { glds16(ap[i] + ko, d + i * 1024); glds16(bp[i] + ko, d + 16384 + i * 1024); }
;     }
;     const char* base = lds + (kt & 1) * GEMM_BUF;
; #pragma unroll
;     for (int ks = 0; ks < 4; ++ks) {
;       const int co = ((2 * ks + hh) ^ swz) * 16;
;       bf16x8 a0 = *(const bf16x8*)(base + roffA + co), a1 = *(const bf16x8*)(base + roffA + 32 * 128 + co);
;       bf16x8 b0 = *(const bf16x8*)(base + roffB + co), b1 = *(const bf16x8*)(base + roffB + 32 * 128 + co);
;       if (SW) {
;         acc[0][0] = mfma32(b0, a0, acc[0][0]); acc[0][1] = mfma32(b1, a0, acc[0][1]);
;         acc[1][0] = mfma32(b0, a1, acc[1][0]); acc[1][1] = mfma32(b1, a1, acc[1][1]);
;       } else {
;         acc[0][0] = mfma32(a0, b0, acc[0][0]); acc[0][1] = mfma32(a0, b1, acc[0][1]);
;         acc[1][0] = mfma32(a1, b0, acc[1][0]); acc[1][1] = mfma32(a1, b1, acc[1][1]);
;       }
;     }
;     asm volatile("s_waitcnt vmcnt(0)" ::: "memory");
;     __syncthreads();
;   }
.LBB0_562:
	s_and_b32 s0, s43, 0x8000
	v_or_b32_e32 v77, s0, v118
	v_add_u32_e32 v85, v77, v119
	ds_read_b128 v[108:111], v85 offset:16384
	ds_read_b128 v[148:151], v85 offset:20480
	v_add_u32_e32 v87, s0, v117
	v_add_u32_e32 v89, v87, v119
	ds_read_b128 v[142:145], v89
	v_add_u32_e32 v85, v77, v120
	s_add_i32 s3, s3, 1
	s_add_i32 s2, s2, 64
	s_cmp_lg_u32 s3, 4
	s_waitcnt lgkmcnt(0)
	v_mfma_f32_32x32x16_bf16 v[48:63], v[108:111], v[142:145], v[48:63]
	s_mov_b32 s43, s44
	v_mfma_f32_32x32x16_bf16 v[32:47], v[148:151], v[142:145], v[32:47]
	ds_read_b128 v[142:145], v89 offset:4096
	v_add_u32_e32 v89, v87, v120
	s_waitcnt lgkmcnt(0)
	v_mfma_f32_32x32x16_bf16 v[16:31], v[108:111], v[142:145], v[16:31]
	ds_read_b128 v[108:111], v85 offset:16384
	v_mfma_f32_32x32x16_bf16 v[0:15], v[148:151], v[142:145], v[0:15]
	ds_read_b128 v[148:151], v85 offset:20480
	ds_read_b128 v[142:145], v89
	v_add_u32_e32 v85, v77, v121
	v_add_u32_e32 v77, v77, v122
	s_waitcnt lgkmcnt(0)
	v_mfma_f32_32x32x16_bf16 v[48:63], v[108:111], v[142:145], v[48:63]
	v_mfma_f32_32x32x16_bf16 v[32:47], v[148:151], v[142:145], v[32:47]
	ds_read_b128 v[142:145], v89 offset:4096
	v_add_u32_e32 v89, v87, v121
	s_waitcnt lgkmcnt(0)
	v_mfma_f32_32x32x16_bf16 v[16:31], v[108:111], v[142:145], v[16:31]
	ds_read_b128 v[108:111], v85 offset:16384
	v_mfma_f32_32x32x16_bf16 v[0:15], v[148:151], v[142:145], v[0:15]
	ds_read_b128 v[148:151], v85 offset:20480
	ds_read_b128 v[142:145], v89
	v_add_u32_e32 v85, v87, v122
	s_waitcnt lgkmcnt(0)
	v_mfma_f32_32x32x16_bf16 v[48:63], v[108:111], v[142:145], v[48:63]
	v_mfma_f32_32x32x16_bf16 v[32:47], v[148:151], v[142:145], v[32:47]
	ds_read_b128 v[142:145], v89 offset:4096
	s_waitcnt lgkmcnt(0)
	v_mfma_f32_32x32x16_bf16 v[16:31], v[108:111], v[142:145], v[16:31]
	ds_read_b128 v[108:111], v77 offset:16384
	v_mfma_f32_32x32x16_bf16 v[0:15], v[148:151], v[142:145], v[0:15]
	ds_read_b128 v[148:151], v77 offset:20480
	ds_read_b128 v[142:145], v85
	s_waitcnt lgkmcnt(0)
	v_mfma_f32_32x32x16_bf16 v[48:63], v[108:111], v[142:145], v[48:63]
	v_mfma_f32_32x32x16_bf16 v[32:47], v[148:151], v[142:145], v[32:47]
	ds_read_b128 v[142:145], v85 offset:4096
	s_waitcnt vmcnt(0)
	s_waitcnt lgkmcnt(0)
	s_barrier
	v_mfma_f32_32x32x16_bf16 v[16:31], v[108:111], v[142:145], v[16:31]
	v_mfma_f32_32x32x16_bf16 v[0:15], v[148:151], v[142:145], v[0:15]
	s_cbranch_scc0 .LBB0_567

; __device__ __forceinline__ f32x16 mfma32(bf16x8 a, bf16x8 b, f32x16 c) { return __builtin_amdgcn_mfma_f32_32x32x16_bf16(a, b, c, 0, 0, 0); }
; template <bool SW>
; __device__ __forceinline__ void gemm_mainloop(const bf16_t* __restrict__ A, int lda, const bf16_t* __restrict__ Bt, int ldb, int K,
;                                               f32x16 (&acc)[2][2], char* lds, int kstart) {
;     ...
;   for (int kt = 0; kt < nk; ++kt) {
;     const bool more = (kt + 1 < nk);
;     if (more) {
;       char* d = ldst + ((kt + 1) & 1) * GEMM_BUF;
;       const int ko = ((kt + 1 + kstart) & (nk - 1)) * 64;
; #pragma unroll
;       for (int i = 0; i < 4; ++i) { glds16(ap[i] + ko, d + i * 1024); glds16(bp[i] + ko, d + 16384 + i * 1024); }
;     }
;     const char* base = lds + (kt & 1) * GEMM_BUF;
; #pragma unroll
;     for (int ks = 0; ks < 4; ++ks) {
;       const int co = ((2 * ks + hh) ^ swz) * 16;
;       bf16x8 a0 = *(const bf16x8*)(base + roffA + co), a1 = *(const bf16x8*)(base + roffA + 32 * 128 + co);
;       bf16x8 b0 = *(const bf16x8*)(base + roffB + co), b1 = *(const bf16x8*)(base + roffB + 32 * 128 + co);
;       if (SW) {
;         acc[0][0] = mfma32(b0, a0, acc[0][0]); acc[0][1] = mfma32(b1, a0, acc[0][1]);
;         acc[1][0] = mfma32(b0, a1, acc[1][0]); acc[1][1] = mfma32(b1, a1, acc[1][1]);
;       } else {
;         acc[0][0] = mfma32(a0, b0, acc[0][0]); acc[0][1] = mfma32(a0, b1, acc[0][1]);
;         acc[1][0] = mfma32(a1, b0, acc[1][0]); acc[1][1] = mfma32(a1, b1, acc[1][1]);
;       }
;     }
;     asm volatile("s_waitcnt vmcnt(0)" ::: "memory");
;     __syncthreads();
;   }
.LBB0_789:
	s_and_b32 s0, s47, 0x8000
	v_or_b32_e32 v77, s0, v106
	v_add_u32_e32 v79, v77, v107
	ds_read_b128 v[118:121], v79 offset:16384
	ds_read_b128 v[126:129], v79 offset:20480
	v_add_u32_e32 v81, s0, v105
	v_add_u32_e32 v83, v81, v107
	ds_read_b128 v[122:125], v83
	v_add_u32_e32 v79, v77, v108
	s_add_i32 s46, s46, 1
	s_add_i32 s45, s45, 64
	s_cmp_lg_u32 s46, 16
	s_waitcnt lgkmcnt(0)
	v_mfma_f32_32x32x16_bf16 v[48:63], v[118:121], v[122:125], v[48:63]
	s_mov_b32 s47, s48
	v_mfma_f32_32x32x16_bf16 v[32:47], v[126:129], v[122:125], v[32:47]
	ds_read_b128 v[122:125], v83 offset:4096
	v_add_u32_e32 v83, v81, v108
	s_waitcnt lgkmcnt(0)
	v_mfma_f32_32x32x16_bf16 v[16:31], v[118:121], v[122:125], v[16:31]
	ds_read_b128 v[118:121], v79 offset:16384
	v_mfma_f32_32x32x16_bf16 v[0:15], v[126:129], v[122:125], v[0:15]
	ds_read_b128 v[126:129], v79 offset:20480
	ds_read_b128 v[122:125], v83
	v_add_u32_e32 v79, v77, v109
	v_add_u32_e32 v77, v77, v110
	s_waitcnt lgkmcnt(0)
	v_mfma_f32_32x32x16_bf16 v[48:63], v[118:121], v[122:125], v[48:63]
	v_mfma_f32_32x32x16_bf16 v[32:47], v[126:129], v[122:125], v[32:47]
	ds_read_b128 v[122:125], v83 offset:4096
	v_add_u32_e32 v83, v81, v109
	s_waitcnt lgkmcnt(0)
	v_mfma_f32_32x32x16_bf16 v[16:31], v[118:121], v[122:125], v[16:31]
	ds_read_b128 v[118:121], v79 offset:16384
	v_mfma_f32_32x32x16_bf16 v[0:15], v[126:129], v[122:125], v[0:15]
	ds_read_b128 v[126:129], v79 offset:20480
	ds_read_b128 v[122:125], v83
	v_add_u32_e32 v79, v81, v110
	s_waitcnt lgkmcnt(0)
	v_mfma_f32_32x32x16_bf16 v[48:63], v[118:121], v[122:125], v[48:63]
	v_mfma_f32_32x32x16_bf16 v[32:47], v[126:129], v[122:125], v[32:47]
	ds_read_b128 v[122:125], v83 offset:4096
	s_waitcnt lgkmcnt(0)
	v_mfma_f32_32x32x16_bf16 v[16:31], v[118:121], v[122:125], v[16:31]
	ds_read_b128 v[118:121], v77 offset:16384
	v_mfma_f32_32x32x16_bf16 v[0:15], v[126:129], v[122:125], v[0:15]
	ds_read_b128 v[126:129], v77 offset:20480
	ds_read_b128 v[122:125], v79
	s_waitcnt lgkmcnt(0)
	v_mfma_f32_32x32x16_bf16 v[48:63], v[118:121], v[122:125], v[48:63]
	v_mfma_f32_32x32x16_bf16 v[32:47], v[126:129], v[122:125], v[32:47]
	ds_read_b128 v[122:125], v79 offset:4096
	s_waitcnt vmcnt(0)
	s_waitcnt lgkmcnt(0)
	s_barrier
	v_mfma_f32_32x32x16_bf16 v[16:31], v[118:121], v[122:125], v[16:31]
	v_mfma_f32_32x32x16_bf16 v[0:15], v[126:129], v[122:125], v[0:15]
	s_cbranch_scc0 .LBB0_794

; __device__ __forceinline__ f32x16 mfma32(bf16x8 a, bf16x8 b, f32x16 c) { return __builtin_amdgcn_mfma_f32_32x32x16_bf16(a, b, c, 0, 0, 0); }
; template <bool SW>
; __device__ __forceinline__ void gemm_mainloop(const bf16_t* __restrict__ A, int lda, const bf16_t* __restrict__ Bt, int ldb, int K,
;                                               f32x16 (&acc)[2][2], char* lds, int kstart) {
;     ...
;   for (int kt = 0; kt < nk; ++kt) {
;     const bool more = (kt + 1 < nk);
;     if (more) {
;       char* d = ldst + ((kt + 1) & 1) * GEMM_BUF;
;       const int ko = ((kt + 1 + kstart) & (nk - 1)) * 64;
; #pragma unroll
;       for (int i = 0; i < 4; ++i) { glds16(ap[i] + ko, d + i * 1024); glds16(bp[i] + ko, d + 16384 + i * 1024); }
;     }
;     const char* base = lds + (kt & 1) * GEMM_BUF;
; #pragma unroll
;     for (int ks = 0; ks < 4; ++ks) {
;       const int co = ((2 * ks + hh) ^ swz) * 16;
;       bf16x8 a0 = *(const bf16x8*)(base + roffA + co), a1 = *(const bf16x8*)(base + roffA + 32 * 128 + co);
;       bf16x8 b0 = *(const bf16x8*)(base + roffB + co), b1 = *(const bf16x8*)(base + roffB + 32 * 128 + co);
;       if (SW) {
;         acc[0][0] = mfma32(b0, a0, acc[0][0]); acc[0][1] = mfma32(b1, a0, acc[0][1]);
;         acc[1][0] = mfma32(b0, a1, acc[1][0]); acc[1][1] = mfma32(b1, a1, acc[1][1]);
;       } else {
;         acc[0][0] = mfma32(a0, b0, acc[0][0]); acc[0][1] = mfma32(a0, b1, acc[0][1]);
;         acc[1][0] = mfma32(a1, b0, acc[1][0]); acc[1][1] = mfma32(a1, b1, acc[1][1]);
;       }
;     }
;     asm volatile("s_waitcnt vmcnt(0)" ::: "memory");
;     __syncthreads();
;   }
.LBB0_795:
	s_and_b32 s0, s39, 0x8000
	v_or_b32_e32 v77, s0, v106
	v_add_u32_e32 v79, v77, v107
	ds_read_b128 v[118:121], v79 offset:16384
	ds_read_b128 v[126:129], v79 offset:20480
	v_add_u32_e32 v81, s0, v105
	v_add_u32_e32 v83, v81, v107
	ds_read_b128 v[122:125], v83
	v_add_u32_e32 v79, v77, v108
	s_add_i32 s38, s38, 1
	s_add_i32 s42, s42, 64
	s_cmp_lg_u32 s38, 16
	s_waitcnt lgkmcnt(0)
	v_mfma_f32_32x32x16_bf16 v[48:63], v[118:121], v[122:125], v[48:63]
	s_mov_b32 s39, s40
	v_mfma_f32_32x32x16_bf16 v[32:47], v[126:129], v[122:125], v[32:47]
	ds_read_b128 v[122:125], v83 offset:4096
	v_add_u32_e32 v83, v81, v108
	s_waitcnt lgkmcnt(0)
	v_mfma_f32_32x32x16_bf16 v[16:31], v[118:121], v[122:125], v[16:31]
	ds_read_b128 v[118:121], v79 offset:16384
	v_mfma_f32_32x32x16_bf16 v[0:15], v[126:129], v[122:125], v[0:15]
	ds_read_b128 v[126:129], v79 offset:20480
	ds_read_b128 v[122:125], v83
	v_add_u32_e32 v79, v77, v109
	v_add_u32_e32 v77, v77, v110
	s_waitcnt lgkmcnt(0)
	v_mfma_f32_32x32x16_bf16 v[48:63], v[118:121], v[122:125], v[48:63]
	v_mfma_f32_32x32x16_bf16 v[32:47], v[126:129], v[122:125], v[32:47]
	ds_read_b128 v[122:125], v83 offset:4096
	v_add_u32_e32 v83, v81, v109
	s_waitcnt lgkmcnt(0)
	v_mfma_f32_32x32x16_bf16 v[16:31], v[118:121], v[122:125], v[16:31]
	ds_read_b128 v[118:121], v79 offset:16384
	v_mfma_f32_32x32x16_bf16 v[0:15], v[126:129], v[122:125], v[0:15]
	ds_read_b128 v[126:129], v79 offset:20480
	ds_read_b128 v[122:125], v83
	v_add_u32_e32 v79, v81, v110
	s_waitcnt lgkmcnt(0)
	v_mfma_f32_32x32x16_bf16 v[48:63], v[118:121], v[122:125], v[48:63]
	v_mfma_f32_32x32x16_bf16 v[32:47], v[126:129], v[122:125], v[32:47]
	ds_read_b128 v[122:125], v83 offset:4096
	s_waitcnt lgkmcnt(0)
	v_mfma_f32_32x32x16_bf16 v[16:31], v[118:121], v[122:125], v[16:31]
	ds_read_b128 v[118:121], v77 offset:16384
	v_mfma_f32_32x32x16_bf16 v[0:15], v[126:129], v[122:125], v[0:15]
	ds_read_b128 v[126:129], v77 offset:20480
	ds_read_b128 v[122:125], v79
	s_waitcnt lgkmcnt(0)
	v_mfma_f32_32x32x16_bf16 v[48:63], v[118:121], v[122:125], v[48:63]
	v_mfma_f32_32x32x16_bf16 v[32:47], v[126:129], v[122:125], v[32:47]
	ds_read_b128 v[122:125], v79 offset:4096
	s_waitcnt vmcnt(0)
	s_waitcnt lgkmcnt(0)
	s_barrier
	v_mfma_f32_32x32x16_bf16 v[16:31], v[118:121], v[122:125], v[16:31]
	v_mfma_f32_32x32x16_bf16 v[0:15], v[126:129], v[122:125], v[0:15]
	s_cbranch_scc0 .LBB0_787

; __device__ __forceinline__ f32x16 mfma32(bf16x8 a, bf16x8 b, f32x16 c) { return __builtin_amdgcn_mfma_f32_32x32x16_bf16(a, b, c, 0, 0, 0); }
; template <bool SW>
; __device__ __forceinline__ void gemm_mainloop(const bf16_t* __restrict__ A, int lda, const bf16_t* __restrict__ Bt, int ldb, int K,
;                                               f32x16 (&acc)[2][2], char* lds, int kstart) {
;     ...
;   for (int kt = 0; kt < nk; ++kt) {
;     const bool more = (kt + 1 < nk);
;     if (more) {
;       char* d = ldst + ((kt + 1) & 1) * GEMM_BUF;
;       const int ko = ((kt + 1 + kstart) & (nk - 1)) * 64;
; #pragma unroll
;       for (int i = 0; i < 4; ++i) { glds16(ap[i] + ko, d + i * 1024); glds16(bp[i] + ko, d + 16384 + i * 1024); }
;     }
;     const char* base = lds + (kt & 1) * GEMM_BUF;
; #pragma unroll
;     for (int ks = 0; ks < 4; ++ks) {
;       const int co = ((2 * ks + hh) ^ swz) * 16;
;       bf16x8 a0 = *(const bf16x8*)(base + roffA + co), a1 = *(const bf16x8*)(base + roffA + 32 * 128 + co);
;       bf16x8 b0 = *(const bf16x8*)(base + roffB + co), b1 = *(const bf16x8*)(base + roffB + 32 * 128 + co);
;       if (SW) {
;         acc[0][0] = mfma32(b0, a0, acc[0][0]); acc[0][1] = mfma32(b1, a0, acc[0][1]);
;         acc[1][0] = mfma32(b0, a1, acc[1][0]); acc[1][1] = mfma32(b1, a1, acc[1][1]);
;       } else {
;         acc[0][0] = mfma32(a0, b0, acc[0][0]); acc[0][1] = mfma32(a0, b1, acc[0][1]);
;         acc[1][0] = mfma32(a1, b0, acc[1][0]); acc[1][1] = mfma32(a1, b1, acc[1][1]);
;       }
;     }
;     asm volatile("s_waitcnt vmcnt(0)" ::: "memory");
;     __syncthreads();
;   }
.LBB0_871:
	s_and_b32 s0, s41, 0x8000
	v_or_b32_e32 v67, s0, v99
	v_add_u32_e32 v71, v67, v100
	ds_read_b128 v[112:115], v71 offset:16384
	ds_read_b128 v[120:123], v71 offset:20480
	v_add_u32_e32 v77, s0, v98
	v_add_u32_e32 v79, v77, v100
	ds_read_b128 v[116:119], v79
	v_add_u32_e32 v71, v67, v101
	s_add_i32 s40, s40, 1
	s_add_i32 s39, s39, 64
	s_cmp_lg_u32 s40, 16
	s_waitcnt lgkmcnt(0)
	v_mfma_f32_32x32x16_bf16 v[48:63], v[112:115], v[116:119], v[48:63]
	s_mov_b32 s41, s42
	v_mfma_f32_32x32x16_bf16 v[32:47], v[120:123], v[116:119], v[32:47]
	ds_read_b128 v[116:119], v79 offset:4096
	v_add_u32_e32 v79, v77, v101
	s_waitcnt lgkmcnt(0)
	v_mfma_f32_32x32x16_bf16 v[16:31], v[112:115], v[116:119], v[16:31]
	ds_read_b128 v[112:115], v71 offset:16384
	v_mfma_f32_32x32x16_bf16 v[0:15], v[120:123], v[116:119], v[0:15]
	ds_read_b128 v[120:123], v71 offset:20480
	ds_read_b128 v[116:119], v79
	v_add_u32_e32 v71, v67, v102
	v_add_u32_e32 v67, v67, v103
	s_waitcnt lgkmcnt(0)
	v_mfma_f32_32x32x16_bf16 v[48:63], v[112:115], v[116:119], v[48:63]
	v_mfma_f32_32x32x16_bf16 v[32:47], v[120:123], v[116:119], v[32:47]
	ds_read_b128 v[116:119], v79 offset:4096
	v_add_u32_e32 v79, v77, v102
	s_waitcnt lgkmcnt(0)
	v_mfma_f32_32x32x16_bf16 v[16:31], v[112:115], v[116:119], v[16:31]
	ds_read_b128 v[112:115], v71 offset:16384
	v_mfma_f32_32x32x16_bf16 v[0:15], v[120:123], v[116:119], v[0:15]
	ds_read_b128 v[120:123], v71 offset:20480
	ds_read_b128 v[116:119], v79
	v_add_u32_e32 v71, v77, v103
	s_waitcnt lgkmcnt(0)
	v_mfma_f32_32x32x16_bf16 v[48:63], v[112:115], v[116:119], v[48:63]
	v_mfma_f32_32x32x16_bf16 v[32:47], v[120:123], v[116:119], v[32:47]
	ds_read_b128 v[116:119], v79 offset:4096
	s_waitcnt lgkmcnt(0)
	v_mfma_f32_32x32x16_bf16 v[16:31], v[112:115], v[116:119], v[16:31]
	ds_read_b128 v[112:115], v67 offset:16384
	v_mfma_f32_32x32x16_bf16 v[0:15], v[120:123], v[116:119], v[0:15]
	ds_read_b128 v[120:123], v67 offset:20480
	ds_read_b128 v[116:119], v71
	s_waitcnt lgkmcnt(0)
	v_mfma_f32_32x32x16_bf16 v[48:63], v[112:115], v[116:119], v[48:63]
	v_mfma_f32_32x32x16_bf16 v[32:47], v[120:123], v[116:119], v[32:47]
	ds_read_b128 v[116:119], v71 offset:4096
	s_waitcnt vmcnt(0)
	s_waitcnt lgkmcnt(0)
	s_barrier
	v_mfma_f32_32x32x16_bf16 v[16:31], v[112:115], v[116:119], v[16:31]
	v_mfma_f32_32x32x16_bf16 v[0:15], v[120:123], v[116:119], v[0:15]
	s_cbranch_scc0 .LBB0_869

; __device__ __forceinline__ f32x16 mfma32(bf16x8 a, bf16x8 b, f32x16 c) { return __builtin_amdgcn_mfma_f32_32x32x16_bf16(a, b, c, 0, 0, 0); }
; template <bool SW>
; __device__ __forceinline__ void gemm_mainloop(const bf16_t* __restrict__ A, int lda, const bf16_t* __restrict__ Bt, int ldb, int K,
;                                               f32x16 (&acc)[2][2], char* lds, int kstart) {
;     ...
;   for (int kt = 0; kt < nk; ++kt) {
;     const bool more = (kt + 1 < nk);
;     if (more) {
;       char* d = ldst + ((kt + 1) & 1) * GEMM_BUF;
;       const int ko = ((kt + 1 + kstart) & (nk - 1)) * 64;
; #pragma unroll
;       for (int i = 0; i < 4; ++i) { glds16(ap[i] + ko, d + i * 1024); glds16(bp[i] + ko, d + 16384 + i * 1024); }
;     }
;     const char* base = lds + (kt & 1) * GEMM_BUF;
; #pragma unroll
;     for (int ks = 0; ks < 4; ++ks) {
;       const int co = ((2 * ks + hh) ^ swz) * 16;
;       bf16x8 a0 = *(const bf16x8*)(base + roffA + co), a1 = *(const bf16x8*)(base + roffA + 32 * 128 + co);
;       bf16x8 b0 = *(const bf16x8*)(base + roffB + co), b1 = *(const bf16x8*)(base + roffB + 32 * 128 + co);
;       if (SW) {
;         acc[0][0] = mfma32(b0, a0, acc[0][0]); acc[0][1] = mfma32(b1, a0, acc[0][1]);
;         acc[1][0] = mfma32(b0, a1, acc[1][0]); acc[1][1] = mfma32(b1, a1, acc[1][1]);
;       } else {
;         acc[0][0] = mfma32(a0, b0, acc[0][0]); acc[0][1] = mfma32(a0, b1, acc[0][1]);
;         acc[1][0] = mfma32(a1, b0, acc[1][0]); acc[1][1] = mfma32(a1, b1, acc[1][1]);
;       }
;     }
;     asm volatile("s_waitcnt vmcnt(0)" ::: "memory");
;     __syncthreads();
;   }
.LBB0_1020:
	s_and_b32 s0, s40, 0x8000
	v_or_b32_e32 v69, s0, v101
	v_add_u32_e32 v73, v69, v102
	ds_read_b128 v[114:117], v73 offset:16384
	ds_read_b128 v[122:125], v73 offset:20480
	v_add_u32_e32 v79, s0, v100
	v_add_u32_e32 v81, v79, v102
	ds_read_b128 v[118:121], v81
	v_add_u32_e32 v73, v69, v103
	s_add_i32 s39, s39, 1
	s_add_i32 s38, s38, 64
	s_cmp_lg_u32 s39, 16
	s_waitcnt lgkmcnt(0)
	v_mfma_f32_32x32x16_bf16 v[48:63], v[114:117], v[118:121], v[48:63]
	s_mov_b32 s40, s41
	v_mfma_f32_32x32x16_bf16 v[32:47], v[122:125], v[118:121], v[32:47]
	ds_read_b128 v[118:121], v81 offset:4096
	v_add_u32_e32 v81, v79, v103
	s_waitcnt lgkmcnt(0)
	v_mfma_f32_32x32x16_bf16 v[16:31], v[114:117], v[118:121], v[16:31]
	ds_read_b128 v[114:117], v73 offset:16384
	v_mfma_f32_32x32x16_bf16 v[0:15], v[122:125], v[118:121], v[0:15]
	ds_read_b128 v[122:125], v73 offset:20480
	ds_read_b128 v[118:121], v81
	v_add_u32_e32 v73, v69, v104
	v_add_u32_e32 v69, v69, v105
	s_waitcnt lgkmcnt(0)
	v_mfma_f32_32x32x16_bf16 v[48:63], v[114:117], v[118:121], v[48:63]
	v_mfma_f32_32x32x16_bf16 v[32:47], v[122:125], v[118:121], v[32:47]
	ds_read_b128 v[118:121], v81 offset:4096
	v_add_u32_e32 v81, v79, v104
	s_waitcnt lgkmcnt(0)
	v_mfma_f32_32x32x16_bf16 v[16:31], v[114:117], v[118:121], v[16:31]
	ds_read_b128 v[114:117], v73 offset:16384
	v_mfma_f32_32x32x16_bf16 v[0:15], v[122:125], v[118:121], v[0:15]
	ds_read_b128 v[122:125], v73 offset:20480
	ds_read_b128 v[118:121], v81
	v_add_u32_e32 v73, v79, v105
	s_waitcnt lgkmcnt(0)
	v_mfma_f32_32x32x16_bf16 v[48:63], v[114:117], v[118:121], v[48:63]
	v_mfma_f32_32x32x16_bf16 v[32:47], v[122:125], v[118:121], v[32:47]
	ds_read_b128 v[118:121], v81 offset:4096
	s_waitcnt lgkmcnt(0)
	v_mfma_f32_32x32x16_bf16 v[16:31], v[114:117], v[118:121], v[16:31]
	ds_read_b128 v[114:117], v69 offset:16384
	v_mfma_f32_32x32x16_bf16 v[0:15], v[122:125], v[118:121], v[0:15]
	ds_read_b128 v[122:125], v69 offset:20480
	ds_read_b128 v[118:121], v73
	s_waitcnt lgkmcnt(0)
	v_mfma_f32_32x32x16_bf16 v[48:63], v[114:117], v[118:121], v[48:63]
	v_mfma_f32_32x32x16_bf16 v[32:47], v[122:125], v[118:121], v[32:47]
	ds_read_b128 v[118:121], v73 offset:4096
	s_waitcnt vmcnt(0)
	s_waitcnt lgkmcnt(0)
	s_barrier
	v_mfma_f32_32x32x16_bf16 v[16:31], v[114:117], v[118:121], v[16:31]
	v_mfma_f32_32x32x16_bf16 v[0:15], v[122:125], v[118:121], v[0:15]
	s_cbranch_scc0 .LBB0_1018
